# code placement: one 4-byte s_nop pad ahead of the first GEMM K-loop (all four K-loops shifted by 4 bytes)
# speedup vs baseline: 1.0126x; 1.0109x over previous
; template <class Epi>
; __device__ __forceinline__ void gemm_phase(LAS unsigned char* lds, const Gemm g, const StaticOrder& S, const Epi& E) {
;     ...
;         const bool has_next = S.next(ui + 1, nxt);
;         const char* nA = has_next ? (const char*)g.A + (size_t)nxt.pm * tstep : cA; const char* nB = has_next ? (const char*)g.Bt + (size_t)nxt.pn * tstep : cB;
;         for (int t = 0; t < nt; t += 2) {
;             const bool last = (t == nt - 2);
;             const char* a1 = cA + (size_t)(t + 1) * kstep;
;             const char* a2 = last ? nA : cA + (size_t)(t + 2) * kstep; const char* b2 = last ? nB : cB + (size_t)(t + 2) * kstep;
;             const char* a3 = a2 + kstep; const char* b3 = b2 + kstep;
.LBB0_163:
	s_add_u32 s70, s60, 0x100
	s_addc_u32 s71, s61, 0
	s_add_u32 s48, s46, 0xb0080
	s_addc_u32 s49, s47, 0
	v_lshl_add_u64 v[136:137], s[48:49], 0, v[132:133]
	v_lshl_add_u64 v[138:139], s[48:49], 0, v[134:135]
	s_mov_b32 s93, -2
	s_mov_b64 s[60:61], 0
	s_nop 0
	s_cmpk_gt_u32 s30, 0xff
	s_cbranch_scc0 .Lprio_164
	s_setprio 1
